# RG-LRU phase prologue: gate-fragment image and parameter rows staged with all loads issued before one wait (was load-wait-write per slice); on top of tables-in-idle-tail + hand-written attention phase
# speedup vs baseline: 1.0168x; 1.0024x over previous
; #define LAS __attribute__((address_space(3)))
; __device__ __forceinline__ void lru_phase(const Ptrs& P, LAS unsigned char* lds, int G, int wave, int lane, int tid) {
;     ...
;     { const int hd0 = blockIdx.x & 15;
;       const v4u* src = (const v4u*)(WGF + (size_t)hd0 * 18432); LAS v4u* dst = (LAS v4u*)(lds + L_WGF);
;       for (int i = tid; i < 2304; i += NT) dst[i] = src[i];
;       const f32x4* ps = (const f32x4*)(PAR + hd0 * 640); LAS f32x4* pd = (LAS f32x4*)(lds + L_PAR);
;       if (tid < 160) pd[tid] = ps[tid]; }
;     __syncthreads();
.LBB0_292:
	s_movk_i32 s7, 0x100
	v_cmp_gt_u32_e64 s[10:11], s7, v184
	s_movk_i32 s7, 0xa0
	v_cmp_gt_u32_e64 s[12:13], s7, v184
	global_load_dwordx4 v[4:7], v[0:1], off
	v_lshl_add_u64 v[0:1], v[0:1], 0, s[4:5]
	global_load_dwordx4 v[8:11], v[0:1], off
	v_lshl_add_u64 v[0:1], v[0:1], 0, s[4:5]
	global_load_dwordx4 v[12:15], v[0:1], off
	v_lshl_add_u64 v[0:1], v[0:1], 0, s[4:5]
	global_load_dwordx4 v[16:19], v[0:1], off
	v_lshl_add_u64 v[0:1], v[0:1], 0, s[4:5]
	s_and_saveexec_b64 s[2:3], s[10:11]
	s_cbranch_execz .Lp2_stage_a
	global_load_dwordx4 v[20:23], v[0:1], off
.Lp2_stage_a:
	s_or_b64 exec, exec, s[2:3]
	s_and_saveexec_b64 s[2:3], s[12:13]
	s_cbranch_execz .Lp2_stage_b
	s_mul_i32 s4, s6, 0xa00
	s_add_u32 s4, s54, s4
	s_addc_u32 s5, s55, 0
	s_add_u32 s4, s4, 0x1d0000
	s_addc_u32 s5, s5, 0
	v_lshl_add_u64 v[24:25], s[4:5], 0, v[186:187]
	global_load_dwordx4 v[26:29], v[24:25], off
.Lp2_stage_b:
	s_or_b64 exec, exec, s[2:3]
	s_waitcnt vmcnt(0)
	ds_write_b128 v3, v[4:7]
	ds_write_b128 v3, v[8:11] offset:8192
	ds_write_b128 v3, v[12:15] offset:16384
	ds_write_b128 v3, v[16:19] offset:24576
	s_and_saveexec_b64 s[2:3], s[10:11]
	s_cbranch_execz .Lp2_stage_c
	ds_write_b128 v3, v[20:23] offset:32768
.Lp2_stage_c:
	s_or_b64 exec, exec, s[2:3]
	s_and_saveexec_b64 s[2:3], s[12:13]
	s_cbranch_execz .LBB0_295
	ds_write_b128 v3, v[26:29] offset:36864
